# v81 + diff loops: the second half of each step's fragment reads alternates with the first ten exps (softmax priority set at the step head)
# speedup vs baseline: 1.0158x; 1.0111x over previous
; #define LAS __attribute__((address_space(3)))
; DI void expsum(f32x16& p, float& l_reg, bf16x8& pa0, bf16x8& pa1) {
; #pragma unroll
;     for (int r = 0; r < 16; ++r) p[r] = __builtin_amdgcn_exp2f(p[r]);
;     float ps = 0.f;
; #pragma unroll
;     for (int r = 0; r < 16; ++r) ps += p[r];
;     l_reg += ps; asm volatile("" : "+v"(l_reg));
;     ...
;     ATT_PK4(p, 0, pa0); ATT_PK4(p, 8, pa1);
;     ...
; }
; DI int v_rd_base(int lane) { return ((lane & 3) << 3) | (((lane >> 2) & 3) << 6) | (((lane >> 4) & 1) << 5) | (((lane >> 5) & 1) << 8); }
; template <int OFF> DI s16x4 tr_read(int vb) { s16x4 r; asm volatile("ds_read_b64_tr_b16 %0, %1 offset:%2" : "=&v"(r) : "v"(vb), "i"(OFF) : "memory"); return r; }
; template <int H> DI void v_reads(s16x4* vf, int vb) {
;     vf[0] = tr_read<v_rd_off(0, 2 * H, 0)>(vb); vf[1] = tr_read<v_rd_off(0, 2 * H, 1)>(vb); vf[2] = tr_read<v_rd_off(0, 2 * H + 1, 0)>(vb); vf[3] = tr_read<v_rd_off(0, 2 * H + 1, 1)>(vb);
;     vf[4] = tr_read<v_rd_off(1, 2 * H, 0)>(vb); vf[5] = tr_read<v_rd_off(1, 2 * H, 1)>(vb); vf[6] = tr_read<v_rd_off(1, 2 * H + 1, 0)>(vb); vf[7] = tr_read<v_rd_off(1, 2 * H + 1, 1)>(vb);
;     vf[8] = tr_read<v_rd_off(2, 2 * H, 0)>(vb); vf[9] = tr_read<v_rd_off(2, 2 * H, 1)>(vb); vf[10] = tr_read<v_rd_off(2, 2 * H + 1, 0)>(vb); vf[11] = tr_read<v_rd_off(2, 2 * H + 1, 1)>(vb);
;     vf[12] = tr_read<v_rd_off(3, 2 * H, 0)>(vb); vf[13] = tr_read<v_rd_off(3, 2 * H, 1)>(vb); vf[14] = tr_read<v_rd_off(3, 2 * H + 1, 0)>(vb); vf[15] = tr_read<v_rd_off(3, 2 * H + 1, 1)>(vb);
; }
; DI void pv_mma(f32x16* o, const s16x4* vf, bf16x8 pa0, bf16x8 pa1) {
;     ...
; #pragma unroll
;     for (int d0 = 0; d0 < 4; ++d0) {
;         o[d0] = __builtin_amdgcn_mfma_f32_32x32x16_bf16(pa0, ATT_PK(vf[4 * d0], vf[4 * d0 + 1]), o[d0], 0, 0, 0);
;         o[d0] = __builtin_amdgcn_mfma_f32_32x32x16_bf16(pa1, ATT_PK(vf[4 * d0 + 2], vf[4 * d0 + 3]), o[d0], 0, 0, 0); }
;     ...
; }
; template <int DQK, int D0A, int D0B> DI void k_reads(bf16x8* kf, const LAS unsigned char* Ks, int half, int r32, int hi) {
; #pragma unroll
;     for (int d0 = D0A; d0 < D0B; ++d0) kf[d0 - D0A] = *(const LAS bf16x8*)(Ks + half * (32 * DQK * 2) + kswz<DQK>(r32, (d0 * 16 + hi * 8) * 2));
; }
; template <int D0A, int D0B> DI void qk_mma(f32x16& p, const bf16x8* kf, const bf16x8* qr) {
; #pragma unroll
;     for (int d0 = D0A; d0 < D0B; ++d0) {
.Lhw_d0_b_n1922:
	s_setprio 1
	ds_read_b128 v[122:125], v196 offset:4096
	ds_read_b128 v[132:135], v197 offset:4096
	s_lshl_b32 s2, s1, 14
	ds_read_b128 v[136:139], v198 offset:4096
	ds_read_b128 v[140:143], v199 offset:4096
	ds_read_b64_tr_b16 v[144:145], v121 offset:0
	ds_read_b64_tr_b16 v[146:147], v121 offset:0x800
	ds_read_b64_tr_b16 v[148:149], v121 offset:0x1000
	ds_read_b64_tr_b16 v[150:151], v121 offset:0x1800
	ds_read_b64_tr_b16 v[152:153], v121 offset:0x200
	ds_read_b64_tr_b16 v[154:155], v121 offset:0xa00
	ds_read_b64_tr_b16 v[156:157], v121 offset:0x1200
	v_exp_f32_e32 v64, v64
	ds_read_b64_tr_b16 v[158:159], v121 offset:0x1a00
	v_exp_f32_e32 v65, v65
	ds_read_b64_tr_b16 v[162:163], v121 offset:0x400
	v_exp_f32_e32 v66, v66
	ds_read_b64_tr_b16 v[164:165], v121 offset:0xc00
	v_exp_f32_e32 v67, v67
	ds_read_b64_tr_b16 v[166:167], v121 offset:0x1400
	v_exp_f32_e32 v68, v68
	ds_read_b64_tr_b16 v[168:169], v121 offset:0x1c00
	v_exp_f32_e32 v69, v69
	ds_read_b64_tr_b16 v[170:171], v121 offset:0x600
	v_exp_f32_e32 v70, v70
	ds_read_b64_tr_b16 v[172:173], v121 offset:0xe00
	v_exp_f32_e32 v71, v71
	ds_read_b64_tr_b16 v[174:175], v121 offset:0x1600
	v_exp_f32_e32 v72, v72
	ds_read_b64_tr_b16 v[176:177], v121 offset:0x1e00
	v_exp_f32_e32 v73, v73
	v_exp_f32_e32 v74, v74
	v_add_f32_e32 v126, v65, v64
	v_exp_f32_e32 v75, v75
	v_add_f32_e32 v126, v66, v126
	v_exp_f32_e32 v76, v76
	v_add_f32_e32 v126, v67, v126
	v_exp_f32_e32 v77, v77
	v_add_f32_e32 v126, v68, v126
	v_exp_f32_e32 v78, v78
	v_add_f32_e32 v126, v69, v126
	v_exp_f32_e32 v79, v79
	v_add_f32_e32 v126, v70, v126
	v_add_f32_e32 v126, v71, v126
	v_add_f32_e32 v126, v72, v126
	v_add_f32_e32 v126, v73, v126
	v_add_f32_e32 v126, v74, v126
	v_add_f32_e32 v126, v75, v126
	v_add_f32_e32 v126, v76, v126
	v_add_f32_e32 v126, v77, v126
	v_add_f32_e32 v126, v78, v126
	v_add_f32_e32 v126, v79, v126
	v_add_f32_e32 v120, v126, v120
	v_cvt_pk_bf16_f32 v64, v64, v65
	v_cvt_pk_bf16_f32 v65, v66, v67
	v_cvt_pk_bf16_f32 v66, v68, v69
	v_cvt_pk_bf16_f32 v67, v70, v71
	v_cvt_pk_bf16_f32 v68, v72, v73
	v_cvt_pk_bf16_f32 v69, v74, v75
	v_cvt_pk_bf16_f32 v70, v76, v77
	v_cvt_pk_bf16_f32 v71, v78, v79
	s_waitcnt lgkmcnt(0)
	s_setprio 2
	v_mfma_f32_32x32x16_bf16 v[0:15], v[64:67], v[144:147], v[0:15]
	s_add_i32 s74, s22, 0xffffc000
	s_and_b32 s74, s74, 0x6000
	s_sub_i32 s3, s0, s98
	s_cmp_lt_u32 s3, s100
	v_mfma_f32_32x32x16_bf16 v[48:63], v[64:67], v[152:155], v[48:63]
	v_mfma_f32_32x32x16_bf16 v[32:47], v[64:67], v[162:165], v[32:47]
	v_mfma_f32_32x32x16_bf16 v[16:31], v[64:67], v[170:173], v[16:31]
	v_mfma_f32_32x32x16_bf16 v[0:15], v[68:71], v[148:151], v[0:15]
	v_mfma_f32_32x32x16_bf16 v[48:63], v[68:71], v[156:159], v[48:63]
	v_mfma_f32_32x32x16_bf16 v[32:47], v[68:71], v[166:169], v[32:47]
	v_mfma_f32_32x32x16_bf16 v[16:31], v[68:71], v[174:177], v[16:31]
	v_add_u32_e32 v196, s74, v107
	v_mfma_f32_32x32x16_bf16 v[64:79], v[122:125], v[92:95], 0
	v_add_u32_e32 v197, s74, v108
	v_mfma_f32_32x32x16_bf16 v[64:79], v[132:135], v[88:91], v[64:79]
	v_add_u32_e32 v198, s74, v109
	v_mfma_f32_32x32x16_bf16 v[64:79], v[136:139], v[84:87], v[64:79]
	v_add_u32_e32 v199, s74, v110
	v_mfma_f32_32x32x16_bf16 v[64:79], v[140:143], v[80:83], v[64:79]
	s_setprio 0
	s_cbranch_scc1 .Lhw_d0_b_dtd0bias1
.Lhw_d0_b_n1924:
	s_setprio 1
	ds_read_b128 v[124:127], v196
	ds_read_b128 v[132:135], v197
	ds_read_b128 v[136:139], v198
	ds_read_b128 v[140:143], v199
	ds_read_b64_tr_b16 v[144:145], v121 offset:0x2000
	ds_read_b64_tr_b16 v[146:147], v121 offset:0x2800
	ds_read_b64_tr_b16 v[148:149], v121 offset:0x3000
	ds_read_b64_tr_b16 v[150:151], v121 offset:0x3800
	ds_read_b64_tr_b16 v[152:153], v121 offset:0x2200
	ds_read_b64_tr_b16 v[154:155], v121 offset:0x2a00
	ds_read_b64_tr_b16 v[156:157], v121 offset:0x3200
	v_exp_f32_e32 v64, v64
	ds_read_b64_tr_b16 v[158:159], v121 offset:0x3a00
	v_exp_f32_e32 v65, v65
	ds_read_b64_tr_b16 v[162:163], v121 offset:0x2400
	v_exp_f32_e32 v66, v66
	ds_read_b64_tr_b16 v[164:165], v121 offset:0x2c00
	v_exp_f32_e32 v67, v67
	ds_read_b64_tr_b16 v[166:167], v121 offset:0x3400
	v_exp_f32_e32 v68, v68
	ds_read_b64_tr_b16 v[168:169], v121 offset:0x3c00
	v_exp_f32_e32 v69, v69
	ds_read_b64_tr_b16 v[170:171], v121 offset:0x2600
	v_exp_f32_e32 v70, v70
	ds_read_b64_tr_b16 v[172:173], v121 offset:0x2e00
	v_exp_f32_e32 v71, v71
	ds_read_b64_tr_b16 v[174:175], v121 offset:0x3600
	v_exp_f32_e32 v72, v72
	ds_read_b64_tr_b16 v[176:177], v121 offset:0x3e00
	v_exp_f32_e32 v73, v73
	v_exp_f32_e32 v74, v74
	v_add_f32_e32 v121, v65, v64
	v_exp_f32_e32 v75, v75
	v_add_f32_e32 v121, v66, v121
	v_exp_f32_e32 v76, v76
	v_add_f32_e32 v121, v67, v121
	v_exp_f32_e32 v77, v77
	v_add_f32_e32 v121, v68, v121
	v_exp_f32_e32 v78, v78
	v_add_f32_e32 v121, v69, v121
	v_exp_f32_e32 v79, v79
	v_add_f32_e32 v121, v70, v121
	v_add_f32_e32 v121, v71, v121
	v_add_f32_e32 v121, v72, v121
	v_add_f32_e32 v121, v73, v121
	v_add_f32_e32 v121, v74, v121
	v_add_f32_e32 v121, v75, v121
	v_add_f32_e32 v121, v76, v121
	v_add_f32_e32 v121, v77, v121
	v_add_f32_e32 v121, v78, v121
	v_add_f32_e32 v121, v79, v121
	v_add_f32_e32 v120, v120, v121
	v_cvt_pk_bf16_f32 v64, v64, v65
	v_cvt_pk_bf16_f32 v65, v66, v67
	v_cvt_pk_bf16_f32 v66, v68, v69
	v_cvt_pk_bf16_f32 v67, v70, v71
	v_cvt_pk_bf16_f32 v68, v72, v73
	v_cvt_pk_bf16_f32 v69, v74, v75
	v_cvt_pk_bf16_f32 v70, v76, v77
	v_cvt_pk_bf16_f32 v71, v78, v79
	s_waitcnt lgkmcnt(0)
	s_setprio 2
	s_waitcnt vmcnt(3)
	s_barrier
	v_mfma_f32_32x32x16_bf16 v[0:15], v[64:67], v[144:147], v[0:15]
	s_sub_i32 s74, s0, s55
	s_cmp_lt_u32 s74, s100
	v_mfma_f32_32x32x16_bf16 v[48:63], v[64:67], v[152:155], v[48:63]
	v_mfma_f32_32x32x16_bf16 v[32:47], v[64:67], v[162:165], v[32:47]
	v_mfma_f32_32x32x16_bf16 v[16:31], v[64:67], v[170:173], v[16:31]
	v_mfma_f32_32x32x16_bf16 v[0:15], v[68:71], v[148:151], v[0:15]
	v_mfma_f32_32x32x16_bf16 v[48:63], v[68:71], v[156:159], v[48:63]
	v_mfma_f32_32x32x16_bf16 v[32:47], v[68:71], v[166:169], v[32:47]
	v_mfma_f32_32x32x16_bf16 v[16:31], v[68:71], v[174:177], v[16:31]
	v_lshl_add_u32 v121, s64, 14, v106
	v_mfma_f32_32x32x16_bf16 v[64:79], v[124:127], v[92:95], 0
	v_add_u32_e32 v100, s8, v100
	v_mfma_f32_32x32x16_bf16 v[64:79], v[132:135], v[88:91], v[64:79]
	v_add_u32_e32 v102, s8, v102
	v_mfma_f32_32x32x16_bf16 v[64:79], v[136:139], v[84:87], v[64:79]
	v_add_u32_e32 v104, s8, v104
	v_mfma_f32_32x32x16_bf16 v[64:79], v[140:143], v[80:83], v[64:79]
	s_cbranch_scc1 .Lhw_d0_b_dtd0bias2

; #define LAS __attribute__((address_space(3)))
; DI void expsum(f32x16& p, float& l_reg, bf16x8& pa0, bf16x8& pa1) {
; #pragma unroll
;     for (int r = 0; r < 16; ++r) p[r] = __builtin_amdgcn_exp2f(p[r]);
;     float ps = 0.f;
; #pragma unroll
;     for (int r = 0; r < 16; ++r) ps += p[r];
;     l_reg += ps; asm volatile("" : "+v"(l_reg));
;     ...
;     ATT_PK4(p, 0, pa0); ATT_PK4(p, 8, pa1);
;     ...
; }
; DI int v_rd_base(int lane) { return ((lane & 3) << 3) | (((lane >> 2) & 3) << 6) | (((lane >> 4) & 1) << 5) | (((lane >> 5) & 1) << 8); }
; template <int OFF> DI s16x4 tr_read(int vb) { s16x4 r; asm volatile("ds_read_b64_tr_b16 %0, %1 offset:%2" : "=&v"(r) : "v"(vb), "i"(OFF) : "memory"); return r; }
; template <int H> DI void v_reads(s16x4* vf, int vb) {
;     vf[0] = tr_read<v_rd_off(0, 2 * H, 0)>(vb); vf[1] = tr_read<v_rd_off(0, 2 * H, 1)>(vb); vf[2] = tr_read<v_rd_off(0, 2 * H + 1, 0)>(vb); vf[3] = tr_read<v_rd_off(0, 2 * H + 1, 1)>(vb);
;     vf[4] = tr_read<v_rd_off(1, 2 * H, 0)>(vb); vf[5] = tr_read<v_rd_off(1, 2 * H, 1)>(vb); vf[6] = tr_read<v_rd_off(1, 2 * H + 1, 0)>(vb); vf[7] = tr_read<v_rd_off(1, 2 * H + 1, 1)>(vb);
;     vf[8] = tr_read<v_rd_off(2, 2 * H, 0)>(vb); vf[9] = tr_read<v_rd_off(2, 2 * H, 1)>(vb); vf[10] = tr_read<v_rd_off(2, 2 * H + 1, 0)>(vb); vf[11] = tr_read<v_rd_off(2, 2 * H + 1, 1)>(vb);
;     vf[12] = tr_read<v_rd_off(3, 2 * H, 0)>(vb); vf[13] = tr_read<v_rd_off(3, 2 * H, 1)>(vb); vf[14] = tr_read<v_rd_off(3, 2 * H + 1, 0)>(vb); vf[15] = tr_read<v_rd_off(3, 2 * H + 1, 1)>(vb);
; }
; DI void pv_mma(f32x16* o, const s16x4* vf, bf16x8 pa0, bf16x8 pa1) {
;     ...
; #pragma unroll
;     for (int d0 = 0; d0 < 4; ++d0) {
;         o[d0] = __builtin_amdgcn_mfma_f32_32x32x16_bf16(pa0, ATT_PK(vf[4 * d0], vf[4 * d0 + 1]), o[d0], 0, 0, 0);
;         o[d0] = __builtin_amdgcn_mfma_f32_32x32x16_bf16(pa1, ATT_PK(vf[4 * d0 + 2], vf[4 * d0 + 3]), o[d0], 0, 0, 0); }
;     ...
; }
; template <int DQK, int D0A, int D0B> DI void k_reads(bf16x8* kf, const LAS unsigned char* Ks, int half, int r32, int hi) {
; #pragma unroll
;     for (int d0 = D0A; d0 < D0B; ++d0) kf[d0 - D0A] = *(const LAS bf16x8*)(Ks + half * (32 * DQK * 2) + kswz<DQK>(r32, (d0 * 16 + hi * 8) * 2));
; }
; template <int D0A, int D0B> DI void qk_mma(f32x16& p, const bf16x8* kf, const bf16x8* qr) {
; #pragma unroll
;     for (int d0 = D0A; d0 < D0B; ++d0) {
.LBB0_1924:
	s_setprio 1
	ds_read_b128 v[124:127], v196
	ds_read_b128 v[132:135], v197
	ds_read_b128 v[136:139], v198
	ds_read_b128 v[140:143], v199
	ds_read_b64_tr_b16 v[144:145], v121 offset:0x2000
	ds_read_b64_tr_b16 v[146:147], v121 offset:0x2800
	ds_read_b64_tr_b16 v[148:149], v121 offset:0x3000
	ds_read_b64_tr_b16 v[150:151], v121 offset:0x3800
	ds_read_b64_tr_b16 v[152:153], v121 offset:0x2200
	ds_read_b64_tr_b16 v[154:155], v121 offset:0x2a00
	ds_read_b64_tr_b16 v[156:157], v121 offset:0x3200
	v_exp_f32_e32 v64, v64
	ds_read_b64_tr_b16 v[158:159], v121 offset:0x3a00
	v_exp_f32_e32 v65, v65
	ds_read_b64_tr_b16 v[162:163], v121 offset:0x2400
	v_exp_f32_e32 v66, v66
	ds_read_b64_tr_b16 v[164:165], v121 offset:0x2c00
	v_exp_f32_e32 v67, v67
	ds_read_b64_tr_b16 v[166:167], v121 offset:0x3400
	v_exp_f32_e32 v68, v68
	ds_read_b64_tr_b16 v[168:169], v121 offset:0x3c00
	v_exp_f32_e32 v69, v69
	ds_read_b64_tr_b16 v[170:171], v121 offset:0x2600
	v_exp_f32_e32 v70, v70
	ds_read_b64_tr_b16 v[172:173], v121 offset:0x2e00
	v_exp_f32_e32 v71, v71
	ds_read_b64_tr_b16 v[174:175], v121 offset:0x3600
	v_exp_f32_e32 v72, v72
	ds_read_b64_tr_b16 v[176:177], v121 offset:0x3e00
	v_exp_f32_e32 v73, v73
	v_exp_f32_e32 v74, v74
	v_add_f32_e32 v121, v65, v64
	v_exp_f32_e32 v75, v75
	v_add_f32_e32 v121, v66, v121
	v_exp_f32_e32 v76, v76
	v_add_f32_e32 v121, v67, v121
	v_exp_f32_e32 v77, v77
	v_add_f32_e32 v121, v68, v121
	v_exp_f32_e32 v78, v78
	v_add_f32_e32 v121, v69, v121
	v_exp_f32_e32 v79, v79
	v_add_f32_e32 v121, v70, v121
	v_add_f32_e32 v121, v71, v121
	v_add_f32_e32 v121, v72, v121
	v_add_f32_e32 v121, v73, v121
	v_add_f32_e32 v121, v74, v121
	v_add_f32_e32 v121, v75, v121
	v_add_f32_e32 v121, v76, v121
	v_add_f32_e32 v121, v77, v121
	v_add_f32_e32 v121, v78, v121
	v_add_f32_e32 v121, v79, v121
	v_add_f32_e32 v120, v120, v121
	v_cvt_pk_bf16_f32 v64, v64, v65
	v_cvt_pk_bf16_f32 v65, v66, v67
	v_cvt_pk_bf16_f32 v66, v68, v69
	v_cvt_pk_bf16_f32 v67, v70, v71
	v_cvt_pk_bf16_f32 v68, v72, v73
	v_cvt_pk_bf16_f32 v69, v74, v75
	v_cvt_pk_bf16_f32 v70, v76, v77
	v_cvt_pk_bf16_f32 v71, v78, v79
	s_waitcnt lgkmcnt(0)
	s_setprio 2
	v_mfma_f32_32x32x16_bf16 v[0:15], v[64:67], v[144:147], v[0:15]
	s_sub_i32 s74, s0, s55
	s_cmp_lt_u32 s74, s100
	v_mfma_f32_32x32x16_bf16 v[48:63], v[64:67], v[152:155], v[48:63]
	v_mfma_f32_32x32x16_bf16 v[32:47], v[64:67], v[162:165], v[32:47]
	v_mfma_f32_32x32x16_bf16 v[16:31], v[64:67], v[170:173], v[16:31]
	v_mfma_f32_32x32x16_bf16 v[0:15], v[68:71], v[148:151], v[0:15]
	v_mfma_f32_32x32x16_bf16 v[48:63], v[68:71], v[156:159], v[48:63]
	v_mfma_f32_32x32x16_bf16 v[32:47], v[68:71], v[166:169], v[32:47]
	v_mfma_f32_32x32x16_bf16 v[16:31], v[68:71], v[174:177], v[16:31]
	v_lshl_add_u32 v121, s64, 14, v106
	v_mfma_f32_32x32x16_bf16 v[64:79], v[124:127], v[92:95], 0
	v_add_u32_e32 v100, s8, v100
	v_mfma_f32_32x32x16_bf16 v[64:79], v[132:135], v[88:91], v[64:79]
	v_add_u32_e32 v102, s8, v102
	v_mfma_f32_32x32x16_bf16 v[64:79], v[136:139], v[84:87], v[64:79]
	v_add_u32_e32 v104, s8, v104
	v_mfma_f32_32x32x16_bf16 v[64:79], v[140:143], v[80:83], v[64:79]
	s_cbranch_scc1 .Ldt_d0_bias2

; #define LAS __attribute__((address_space(3)))
; DI void expsum(f32x16& p, float& l_reg, bf16x8& pa0, bf16x8& pa1) {
; #pragma unroll
;     for (int r = 0; r < 16; ++r) p[r] = __builtin_amdgcn_exp2f(p[r]);
;     float ps = 0.f;
; #pragma unroll
;     for (int r = 0; r < 16; ++r) ps += p[r];
;     l_reg += ps; asm volatile("" : "+v"(l_reg));
;     ...
;     ATT_PK4(p, 0, pa0); ATT_PK4(p, 8, pa1);
;     ...
; }
; DI int v_rd_base(int lane) { return ((lane & 3) << 3) | (((lane >> 2) & 3) << 6) | (((lane >> 4) & 1) << 5) | (((lane >> 5) & 1) << 8); }
; template <int OFF> DI s16x4 tr_read(int vb) { s16x4 r; asm volatile("ds_read_b64_tr_b16 %0, %1 offset:%2" : "=&v"(r) : "v"(vb), "i"(OFF) : "memory"); return r; }
; template <int H> DI void v_reads(s16x4* vf, int vb) {
;     vf[0] = tr_read<v_rd_off(0, 2 * H, 0)>(vb); vf[1] = tr_read<v_rd_off(0, 2 * H, 1)>(vb); vf[2] = tr_read<v_rd_off(0, 2 * H + 1, 0)>(vb); vf[3] = tr_read<v_rd_off(0, 2 * H + 1, 1)>(vb);
;     vf[4] = tr_read<v_rd_off(1, 2 * H, 0)>(vb); vf[5] = tr_read<v_rd_off(1, 2 * H, 1)>(vb); vf[6] = tr_read<v_rd_off(1, 2 * H + 1, 0)>(vb); vf[7] = tr_read<v_rd_off(1, 2 * H + 1, 1)>(vb);
;     vf[8] = tr_read<v_rd_off(2, 2 * H, 0)>(vb); vf[9] = tr_read<v_rd_off(2, 2 * H, 1)>(vb); vf[10] = tr_read<v_rd_off(2, 2 * H + 1, 0)>(vb); vf[11] = tr_read<v_rd_off(2, 2 * H + 1, 1)>(vb);
;     vf[12] = tr_read<v_rd_off(3, 2 * H, 0)>(vb); vf[13] = tr_read<v_rd_off(3, 2 * H, 1)>(vb); vf[14] = tr_read<v_rd_off(3, 2 * H + 1, 0)>(vb); vf[15] = tr_read<v_rd_off(3, 2 * H + 1, 1)>(vb);
; }
; DI void pv_mma(f32x16* o, const s16x4* vf, bf16x8 pa0, bf16x8 pa1) {
;     ...
; #pragma unroll
;     for (int d0 = 0; d0 < 4; ++d0) {
;         o[d0] = __builtin_amdgcn_mfma_f32_32x32x16_bf16(pa0, ATT_PK(vf[4 * d0], vf[4 * d0 + 1]), o[d0], 0, 0, 0);
;         o[d0] = __builtin_amdgcn_mfma_f32_32x32x16_bf16(pa1, ATT_PK(vf[4 * d0 + 2], vf[4 * d0 + 3]), o[d0], 0, 0, 0); }
;     ...
; }
; template <int DQK, int D0A, int D0B> DI void k_reads(bf16x8* kf, const LAS unsigned char* Ks, int half, int r32, int hi) {
; #pragma unroll
;     for (int d0 = D0A; d0 < D0B; ++d0) kf[d0 - D0A] = *(const LAS bf16x8*)(Ks + half * (32 * DQK * 2) + kswz<DQK>(r32, (d0 * 16 + hi * 8) * 2));
; }
; template <int D0A, int D0B> DI void qk_mma(f32x16& p, const bf16x8* kf, const bf16x8* qr) {
; #pragma unroll
;     for (int d0 = D0A; d0 < D0B; ++d0) {
.Lhw_d1_b_n1953:
	s_setprio 1
	ds_read_b128 v[122:125], v196 offset:4096
	ds_read_b128 v[132:135], v197 offset:4096
	s_lshl_b32 s2, s23, 14
	ds_read_b128 v[136:139], v198 offset:4096
	ds_read_b128 v[140:143], v199 offset:4096
	ds_read_b64_tr_b16 v[144:145], v121 offset:0
	ds_read_b64_tr_b16 v[146:147], v121 offset:0x800
	ds_read_b64_tr_b16 v[148:149], v121 offset:0x1000
	ds_read_b64_tr_b16 v[150:151], v121 offset:0x1800
	ds_read_b64_tr_b16 v[152:153], v121 offset:0x200
	ds_read_b64_tr_b16 v[154:155], v121 offset:0xa00
	ds_read_b64_tr_b16 v[156:157], v121 offset:0x1200
	v_exp_f32_e32 v64, v64
	ds_read_b64_tr_b16 v[158:159], v121 offset:0x1a00
	v_exp_f32_e32 v65, v65
	ds_read_b64_tr_b16 v[162:163], v121 offset:0x400
	v_exp_f32_e32 v66, v66
	ds_read_b64_tr_b16 v[164:165], v121 offset:0xc00
	v_exp_f32_e32 v67, v67
	ds_read_b64_tr_b16 v[166:167], v121 offset:0x1400
	v_exp_f32_e32 v68, v68
	ds_read_b64_tr_b16 v[168:169], v121 offset:0x1c00
	v_exp_f32_e32 v69, v69
	ds_read_b64_tr_b16 v[170:171], v121 offset:0x600
	v_exp_f32_e32 v70, v70
	ds_read_b64_tr_b16 v[172:173], v121 offset:0xe00
	v_exp_f32_e32 v71, v71
	ds_read_b64_tr_b16 v[174:175], v121 offset:0x1600
	v_exp_f32_e32 v72, v72
	ds_read_b64_tr_b16 v[176:177], v121 offset:0x1e00
	v_exp_f32_e32 v73, v73
	v_exp_f32_e32 v74, v74
	v_add_f32_e32 v126, v65, v64
	v_exp_f32_e32 v75, v75
	v_add_f32_e32 v126, v66, v126
	v_exp_f32_e32 v76, v76
	v_add_f32_e32 v126, v67, v126
	v_exp_f32_e32 v77, v77
	v_add_f32_e32 v126, v68, v126
	v_exp_f32_e32 v78, v78
	v_add_f32_e32 v126, v69, v126
	v_exp_f32_e32 v79, v79
	v_add_f32_e32 v126, v70, v126
	v_add_f32_e32 v126, v71, v126
	v_add_f32_e32 v126, v72, v126
	v_add_f32_e32 v126, v73, v126
	v_add_f32_e32 v126, v74, v126
	v_add_f32_e32 v126, v75, v126
	v_add_f32_e32 v126, v76, v126
	v_add_f32_e32 v126, v77, v126
	v_add_f32_e32 v126, v78, v126
	v_add_f32_e32 v126, v79, v126
	v_add_f32_e32 v120, v126, v120
	v_cvt_pk_bf16_f32 v64, v64, v65
	v_cvt_pk_bf16_f32 v65, v66, v67
	v_cvt_pk_bf16_f32 v66, v68, v69
	v_cvt_pk_bf16_f32 v67, v70, v71
	v_cvt_pk_bf16_f32 v68, v72, v73
	v_cvt_pk_bf16_f32 v69, v74, v75
	v_cvt_pk_bf16_f32 v70, v76, v77
	v_cvt_pk_bf16_f32 v71, v78, v79
	s_waitcnt lgkmcnt(0)
	s_setprio 2
	v_mfma_f32_32x32x16_bf16 v[0:15], v[64:67], v[144:147], v[0:15]
	s_add_i32 s74, s22, 0xffffc000
	s_and_b32 s74, s74, 0x6000
	s_sub_i32 s3, s0, s98
	s_cmp_lt_u32 s3, s100
	v_mfma_f32_32x32x16_bf16 v[48:63], v[64:67], v[152:155], v[48:63]
	v_mfma_f32_32x32x16_bf16 v[16:31], v[64:67], v[162:165], v[16:31]
	v_mfma_f32_32x32x16_bf16 v[32:47], v[64:67], v[170:173], v[32:47]
	v_mfma_f32_32x32x16_bf16 v[0:15], v[68:71], v[148:151], v[0:15]
	v_mfma_f32_32x32x16_bf16 v[48:63], v[68:71], v[156:159], v[48:63]
	v_mfma_f32_32x32x16_bf16 v[16:31], v[68:71], v[166:169], v[16:31]
	v_mfma_f32_32x32x16_bf16 v[32:47], v[68:71], v[174:177], v[32:47]
	v_add_u32_e32 v196, s74, v107
	v_mfma_f32_32x32x16_bf16 v[64:79], v[122:125], v[92:95], 0
	v_add_u32_e32 v197, s74, v108
	v_mfma_f32_32x32x16_bf16 v[64:79], v[132:135], v[88:91], v[64:79]
	v_add_u32_e32 v198, s74, v109
	v_mfma_f32_32x32x16_bf16 v[64:79], v[136:139], v[84:87], v[64:79]
	v_add_u32_e32 v199, s74, v110
	v_mfma_f32_32x32x16_bf16 v[64:79], v[140:143], v[80:83], v[64:79]
	s_setprio 0
	s_cbranch_scc1 .Lhw_d1_b_dtd1bias1
.Lhw_d1_b_n1955:
	s_setprio 1
	ds_read_b128 v[124:127], v196
	ds_read_b128 v[132:135], v197
	ds_read_b128 v[136:139], v198
	ds_read_b128 v[140:143], v199
	ds_read_b64_tr_b16 v[144:145], v121 offset:0x2000
	ds_read_b64_tr_b16 v[146:147], v121 offset:0x2800
	ds_read_b64_tr_b16 v[148:149], v121 offset:0x3000
	ds_read_b64_tr_b16 v[150:151], v121 offset:0x3800
	ds_read_b64_tr_b16 v[152:153], v121 offset:0x2200
	ds_read_b64_tr_b16 v[154:155], v121 offset:0x2a00
	ds_read_b64_tr_b16 v[156:157], v121 offset:0x3200
	v_exp_f32_e32 v64, v64
	ds_read_b64_tr_b16 v[158:159], v121 offset:0x3a00
	v_exp_f32_e32 v65, v65
	ds_read_b64_tr_b16 v[162:163], v121 offset:0x2400
	v_exp_f32_e32 v66, v66
	ds_read_b64_tr_b16 v[164:165], v121 offset:0x2c00
	v_exp_f32_e32 v67, v67
	ds_read_b64_tr_b16 v[166:167], v121 offset:0x3400
	v_exp_f32_e32 v68, v68
	ds_read_b64_tr_b16 v[168:169], v121 offset:0x3c00
	v_exp_f32_e32 v69, v69
	ds_read_b64_tr_b16 v[170:171], v121 offset:0x2600
	v_exp_f32_e32 v70, v70
	ds_read_b64_tr_b16 v[172:173], v121 offset:0x2e00
	v_exp_f32_e32 v71, v71
	ds_read_b64_tr_b16 v[174:175], v121 offset:0x3600
	v_exp_f32_e32 v72, v72
	ds_read_b64_tr_b16 v[176:177], v121 offset:0x3e00
	v_exp_f32_e32 v73, v73
	v_exp_f32_e32 v74, v74
	v_add_f32_e32 v121, v65, v64
	v_exp_f32_e32 v75, v75
	v_add_f32_e32 v121, v66, v121
	v_exp_f32_e32 v76, v76
	v_add_f32_e32 v121, v67, v121
	v_exp_f32_e32 v77, v77
	v_add_f32_e32 v121, v68, v121
	v_exp_f32_e32 v78, v78
	v_add_f32_e32 v121, v69, v121
	v_exp_f32_e32 v79, v79
	v_add_f32_e32 v121, v70, v121
	v_add_f32_e32 v121, v71, v121
	v_add_f32_e32 v121, v72, v121
	v_add_f32_e32 v121, v73, v121
	v_add_f32_e32 v121, v74, v121
	v_add_f32_e32 v121, v75, v121
	v_add_f32_e32 v121, v76, v121
	v_add_f32_e32 v121, v77, v121
	v_add_f32_e32 v121, v78, v121
	v_add_f32_e32 v121, v79, v121
	v_add_f32_e32 v120, v120, v121
	v_cvt_pk_bf16_f32 v64, v64, v65
	v_cvt_pk_bf16_f32 v65, v66, v67
	v_cvt_pk_bf16_f32 v66, v68, v69
	v_cvt_pk_bf16_f32 v67, v70, v71
	v_cvt_pk_bf16_f32 v68, v72, v73
	v_cvt_pk_bf16_f32 v69, v74, v75
	v_cvt_pk_bf16_f32 v70, v76, v77
	v_cvt_pk_bf16_f32 v71, v78, v79
	s_waitcnt lgkmcnt(0)
	s_setprio 2
	s_waitcnt vmcnt(3)
	s_barrier
	v_mfma_f32_32x32x16_bf16 v[0:15], v[64:67], v[144:147], v[0:15]
	s_sub_i32 s74, s0, s47
	s_cmp_lt_u32 s74, s100
	v_mfma_f32_32x32x16_bf16 v[48:63], v[64:67], v[152:155], v[48:63]
	v_mfma_f32_32x32x16_bf16 v[16:31], v[64:67], v[162:165], v[16:31]
	v_mfma_f32_32x32x16_bf16 v[32:47], v[64:67], v[170:173], v[32:47]
	v_mfma_f32_32x32x16_bf16 v[0:15], v[68:71], v[148:151], v[0:15]
	v_mfma_f32_32x32x16_bf16 v[48:63], v[68:71], v[156:159], v[48:63]
	v_mfma_f32_32x32x16_bf16 v[16:31], v[68:71], v[166:169], v[16:31]
	v_mfma_f32_32x32x16_bf16 v[32:47], v[68:71], v[174:177], v[32:47]
	v_lshl_add_u32 v121, s49, 14, v106
	v_mfma_f32_32x32x16_bf16 v[64:79], v[124:127], v[92:95], 0
	v_add_u32_e32 v100, s8, v100
	v_mfma_f32_32x32x16_bf16 v[64:79], v[132:135], v[88:91], v[64:79]
	v_add_u32_e32 v102, s8, v102
	v_mfma_f32_32x32x16_bf16 v[64:79], v[136:139], v[84:87], v[64:79]
	v_add_u32_e32 v104, s8, v104
	v_mfma_f32_32x32x16_bf16 v[64:79], v[140:143], v[80:83], v[64:79]
	s_cbranch_scc1 .Lhw_d1_b_dtd1bias2

; #define LAS __attribute__((address_space(3)))
; DI void expsum(f32x16& p, float& l_reg, bf16x8& pa0, bf16x8& pa1) {
; #pragma unroll
;     for (int r = 0; r < 16; ++r) p[r] = __builtin_amdgcn_exp2f(p[r]);
;     float ps = 0.f;
; #pragma unroll
;     for (int r = 0; r < 16; ++r) ps += p[r];
;     l_reg += ps; asm volatile("" : "+v"(l_reg));
;     ...
;     ATT_PK4(p, 0, pa0); ATT_PK4(p, 8, pa1);
;     ...
; }
; DI int v_rd_base(int lane) { return ((lane & 3) << 3) | (((lane >> 2) & 3) << 6) | (((lane >> 4) & 1) << 5) | (((lane >> 5) & 1) << 8); }
; template <int OFF> DI s16x4 tr_read(int vb) { s16x4 r; asm volatile("ds_read_b64_tr_b16 %0, %1 offset:%2" : "=&v"(r) : "v"(vb), "i"(OFF) : "memory"); return r; }
; template <int H> DI void v_reads(s16x4* vf, int vb) {
;     vf[0] = tr_read<v_rd_off(0, 2 * H, 0)>(vb); vf[1] = tr_read<v_rd_off(0, 2 * H, 1)>(vb); vf[2] = tr_read<v_rd_off(0, 2 * H + 1, 0)>(vb); vf[3] = tr_read<v_rd_off(0, 2 * H + 1, 1)>(vb);
;     vf[4] = tr_read<v_rd_off(1, 2 * H, 0)>(vb); vf[5] = tr_read<v_rd_off(1, 2 * H, 1)>(vb); vf[6] = tr_read<v_rd_off(1, 2 * H + 1, 0)>(vb); vf[7] = tr_read<v_rd_off(1, 2 * H + 1, 1)>(vb);
;     vf[8] = tr_read<v_rd_off(2, 2 * H, 0)>(vb); vf[9] = tr_read<v_rd_off(2, 2 * H, 1)>(vb); vf[10] = tr_read<v_rd_off(2, 2 * H + 1, 0)>(vb); vf[11] = tr_read<v_rd_off(2, 2 * H + 1, 1)>(vb);
;     vf[12] = tr_read<v_rd_off(3, 2 * H, 0)>(vb); vf[13] = tr_read<v_rd_off(3, 2 * H, 1)>(vb); vf[14] = tr_read<v_rd_off(3, 2 * H + 1, 0)>(vb); vf[15] = tr_read<v_rd_off(3, 2 * H + 1, 1)>(vb);
; }
; DI void pv_mma(f32x16* o, const s16x4* vf, bf16x8 pa0, bf16x8 pa1) {
;     ...
; #pragma unroll
;     for (int d0 = 0; d0 < 4; ++d0) {
;         o[d0] = __builtin_amdgcn_mfma_f32_32x32x16_bf16(pa0, ATT_PK(vf[4 * d0], vf[4 * d0 + 1]), o[d0], 0, 0, 0);
;         o[d0] = __builtin_amdgcn_mfma_f32_32x32x16_bf16(pa1, ATT_PK(vf[4 * d0 + 2], vf[4 * d0 + 3]), o[d0], 0, 0, 0); }
;     ...
; }
; template <int DQK, int D0A, int D0B> DI void k_reads(bf16x8* kf, const LAS unsigned char* Ks, int half, int r32, int hi) {
; #pragma unroll
;     for (int d0 = D0A; d0 < D0B; ++d0) kf[d0 - D0A] = *(const LAS bf16x8*)(Ks + half * (32 * DQK * 2) + kswz<DQK>(r32, (d0 * 16 + hi * 8) * 2));
; }
; template <int D0A, int D0B> DI void qk_mma(f32x16& p, const bf16x8* kf, const bf16x8* qr) {
; #pragma unroll
;     for (int d0 = D0A; d0 < D0B; ++d0) {
.LBB0_1955:
	s_setprio 1
	ds_read_b128 v[124:127], v196
	ds_read_b128 v[132:135], v197
	ds_read_b128 v[136:139], v198
	ds_read_b128 v[140:143], v199
	ds_read_b64_tr_b16 v[144:145], v121 offset:0x2000
	ds_read_b64_tr_b16 v[146:147], v121 offset:0x2800
	ds_read_b64_tr_b16 v[148:149], v121 offset:0x3000
	ds_read_b64_tr_b16 v[150:151], v121 offset:0x3800
	ds_read_b64_tr_b16 v[152:153], v121 offset:0x2200
	ds_read_b64_tr_b16 v[154:155], v121 offset:0x2a00
	ds_read_b64_tr_b16 v[156:157], v121 offset:0x3200
	v_exp_f32_e32 v64, v64
	ds_read_b64_tr_b16 v[158:159], v121 offset:0x3a00
	v_exp_f32_e32 v65, v65
	ds_read_b64_tr_b16 v[162:163], v121 offset:0x2400
	v_exp_f32_e32 v66, v66
	ds_read_b64_tr_b16 v[164:165], v121 offset:0x2c00
	v_exp_f32_e32 v67, v67
	ds_read_b64_tr_b16 v[166:167], v121 offset:0x3400
	v_exp_f32_e32 v68, v68
	ds_read_b64_tr_b16 v[168:169], v121 offset:0x3c00
	v_exp_f32_e32 v69, v69
	ds_read_b64_tr_b16 v[170:171], v121 offset:0x2600
	v_exp_f32_e32 v70, v70
	ds_read_b64_tr_b16 v[172:173], v121 offset:0x2e00
	v_exp_f32_e32 v71, v71
	ds_read_b64_tr_b16 v[174:175], v121 offset:0x3600
	v_exp_f32_e32 v72, v72
	ds_read_b64_tr_b16 v[176:177], v121 offset:0x3e00
	v_exp_f32_e32 v73, v73
	v_exp_f32_e32 v74, v74
	v_add_f32_e32 v121, v65, v64
	v_exp_f32_e32 v75, v75
	v_add_f32_e32 v121, v66, v121
	v_exp_f32_e32 v76, v76
	v_add_f32_e32 v121, v67, v121
	v_exp_f32_e32 v77, v77
	v_add_f32_e32 v121, v68, v121
	v_exp_f32_e32 v78, v78
	v_add_f32_e32 v121, v69, v121
	v_exp_f32_e32 v79, v79
	v_add_f32_e32 v121, v70, v121
	v_add_f32_e32 v121, v71, v121
	v_add_f32_e32 v121, v72, v121
	v_add_f32_e32 v121, v73, v121
	v_add_f32_e32 v121, v74, v121
	v_add_f32_e32 v121, v75, v121
	v_add_f32_e32 v121, v76, v121
	v_add_f32_e32 v121, v77, v121
	v_add_f32_e32 v121, v78, v121
	v_add_f32_e32 v121, v79, v121
	v_add_f32_e32 v120, v120, v121
	v_cvt_pk_bf16_f32 v64, v64, v65
	v_cvt_pk_bf16_f32 v65, v66, v67
	v_cvt_pk_bf16_f32 v66, v68, v69
	v_cvt_pk_bf16_f32 v67, v70, v71
	v_cvt_pk_bf16_f32 v68, v72, v73
	v_cvt_pk_bf16_f32 v69, v74, v75
	v_cvt_pk_bf16_f32 v70, v76, v77
	v_cvt_pk_bf16_f32 v71, v78, v79
	s_waitcnt lgkmcnt(0)
	s_setprio 2
	v_mfma_f32_32x32x16_bf16 v[0:15], v[64:67], v[144:147], v[0:15]
	s_sub_i32 s74, s0, s47
	s_cmp_lt_u32 s74, s100
	v_mfma_f32_32x32x16_bf16 v[48:63], v[64:67], v[152:155], v[48:63]
	v_mfma_f32_32x32x16_bf16 v[16:31], v[64:67], v[162:165], v[16:31]
	v_mfma_f32_32x32x16_bf16 v[32:47], v[64:67], v[170:173], v[32:47]
	v_mfma_f32_32x32x16_bf16 v[0:15], v[68:71], v[148:151], v[0:15]
	v_mfma_f32_32x32x16_bf16 v[48:63], v[68:71], v[156:159], v[48:63]
	v_mfma_f32_32x32x16_bf16 v[16:31], v[68:71], v[166:169], v[16:31]
	v_mfma_f32_32x32x16_bf16 v[32:47], v[68:71], v[174:177], v[32:47]
	v_lshl_add_u32 v121, s49, 14, v106
	v_mfma_f32_32x32x16_bf16 v[64:79], v[124:127], v[92:95], 0
	v_add_u32_e32 v100, s8, v100
	v_mfma_f32_32x32x16_bf16 v[64:79], v[132:135], v[88:91], v[64:79]
	v_add_u32_e32 v102, s8, v102
	v_mfma_f32_32x32x16_bf16 v[64:79], v[136:139], v[84:87], v[64:79]
	v_add_u32_e32 v104, s8, v104
	v_mfma_f32_32x32x16_bf16 v[64:79], v[140:143], v[80:83], v[64:79]
	s_cbranch_scc1 .Ldt_d1_bias2
